# FFN-up k-loop: copy of the loop without exec writes, taken when all four row-group masks are full
# baseline (speedup 1.0000x reference)
.LBB0_669:
	s_or_b64 exec, exec, s[18:19]
	v_add_co_u32_e32 v4, vcc, 0x7000, v30
	s_mul_i32 s18, s52, 62
	s_nop 0
	v_addc_co_u32_e32 v5, vcc, 0, v31, vcc
	global_load_dwordx4 v[110:113], v[4:5], off
	v_ashrrev_i32_e32 v4, 3, v41
	s_add_i32 s18, s3, s18
	v_lshrrev_b32_e32 v116, 4, v4
	s_add_i32 s18, s18, s51
	v_ashrrev_i32_e32 v8, 3, v40
	v_lshlrev_b64 v[4:5], 18, v[116:117]
	s_lshl_b32 s18, s18, 1
	v_lshl_add_u64 v[2:3], v[2:3], 1, v[4:5]
	v_lshrrev_b32_e32 v116, 4, v8
	v_subrev_u16_e32 v4, s18, v163
	v_ashrrev_i32_e32 v7, 3, v39
	v_lshl_add_u64 v[128:129], v[122:123], 0, v[2:3]
	v_lshlrev_b64 v[2:3], 18, v[116:117]
	v_and_b32_e32 v4, 0x7f, v4
	s_waitcnt lgkmcnt(0)
	s_barrier
	ds_read_b128 v[102:105], v168 offset:18432
	ds_read_b128 v[94:97], v168 offset:23040
	ds_read_b128 v[106:109], v169
	ds_read_b128 v[98:101], v169 offset:4608
	v_lshl_or_b32 v2, v4, 7, v2
	v_lshrrev_b32_e32 v116, 4, v7
	v_subrev_u16_e32 v4, s18, v164
	v_ashrrev_i32_e32 v6, 3, v38
	v_lshl_add_u64 v[130:131], v[122:123], 0, v[2:3]
	v_lshlrev_b64 v[2:3], 18, v[116:117]
	v_and_b32_e32 v4, 0x7f, v4
	v_lshl_or_b32 v2, v4, 7, v2
	v_lshrrev_b32_e32 v116, 4, v6
	v_subrev_u16_e32 v4, s18, v165
	v_lshl_add_u64 v[132:133], v[122:123], 0, v[2:3]
	v_lshlrev_b64 v[2:3], 18, v[116:117]
	v_and_b32_e32 v4, 0x7f, v4
	v_lshl_or_b32 v2, v4, 7, v2
	v_lshl_add_u64 v[134:135], v[122:123], 0, v[2:3]
	s_mov_b32 s15, 0
	v_lshl_add_u64 v[136:137], v[124:125], 0, s[16:17]
	s_mov_b64 s[16:17], 0
	s_sub_u32 s62, 0x102c000, s34
	v_add_u32_e32 v220, s62, v136
	s_sub_u32 s62, 0x102d000, s34
	v_add_u32_e32 v221, s62, v136
	s_sub_u32 s62, 0x102e000, s34
	v_add_u32_e32 v222, s62, v136
	s_sub_u32 s62, 0x102f000, s34
	v_add_u32_e32 v223, s62, v136
	v_subrev_u32_e32 v224, s34, v134
	v_subrev_u32_e32 v225, s34, v132
	v_subrev_u32_e32 v226, s34, v130
	v_subrev_u32_e32 v227, s34, v128
	s_mov_b32 s64, s34
	s_mov_b32 s65, s35
	s_mov_b32 s66, 6
	s_and_b64 s[62:63], s[4:5], s[6:7]
	s_and_b64 s[62:63], s[62:63], s[8:9]
	s_and_b64 s[62:63], s[62:63], s[10:11]
	s_cmp_eq_u64 s[62:63], -1
	s_cbranch_scc0 .Lk5_masked
	ds_read_b128 v[172:175], v168 offset:18464
	ds_read_b128 v[176:179], v168 offset:23072
	ds_read_b128 v[180:183], v169 offset:32
	ds_read_b128 v[184:187], v169 offset:4640
	s_waitcnt lgkmcnt(4)
	v_mfma_f32_32x32x16_bf16 v[50:65], v[102:105], v[106:109], 0
	s_waitcnt vmcnt(7)
	ds_write_b128 v140, v[66:69] offset:36864
	v_mfma_f32_32x32x16_bf16 v[34:49], v[94:97], v[106:109], 0
	s_waitcnt vmcnt(6)
	ds_write_b128 v140, v[74:77] offset:55296
	v_mfma_f32_32x32x16_bf16 v[18:33], v[102:105], v[98:101], 0
	s_waitcnt vmcnt(5)
	ds_write_b128 v142, v[70:73] offset:36864
	v_mfma_f32_32x32x16_bf16 v[2:17], v[94:97], v[98:101], 0
	s_waitcnt vmcnt(4)
	ds_write_b128 v142, v[82:85] offset:55296
	ds_read_b128 v[102:105], v168 offset:18496
	ds_read_b128 v[94:97], v168 offset:23104
	ds_read_b128 v[106:109], v169 offset:64
	ds_read_b128 v[98:101], v169 offset:4672
	s_waitcnt lgkmcnt(4)
	v_mfma_f32_32x32x16_bf16 v[50:65], v[172:175], v[180:183], v[50:65]
	s_waitcnt vmcnt(3)
	ds_write_b128 v144, v[78:81] offset:36864
	v_mfma_f32_32x32x16_bf16 v[34:49], v[176:179], v[180:183], v[34:49]
	s_waitcnt vmcnt(2)
	ds_write_b128 v144, v[86:89] offset:55296
	v_mfma_f32_32x32x16_bf16 v[18:33], v[172:175], v[184:187], v[18:33]
	s_waitcnt vmcnt(1)
	ds_write_b128 v146, v[90:93] offset:36864
	v_mfma_f32_32x32x16_bf16 v[2:17], v[176:179], v[184:187], v[2:17]
	s_waitcnt vmcnt(0)
	ds_write_b128 v146, v[110:113] offset:55296
	ds_read_b128 v[172:175], v168 offset:18528
	ds_read_b128 v[176:179], v168 offset:23136
	ds_read_b128 v[180:183], v169 offset:96
	ds_read_b128 v[184:187], v169 offset:4704
	s_waitcnt lgkmcnt(8)
	v_mfma_f32_32x32x16_bf16 v[50:65], v[102:105], v[106:109], v[50:65]
	global_load_dwordx4 v[66:69], v224, s[64:65]
	global_load_dwordx4 v[74:77], v220, s[64:65]
	v_mfma_f32_32x32x16_bf16 v[34:49], v[94:97], v[106:109], v[34:49]
	global_load_dwordx4 v[70:73], v225, s[64:65]
	global_load_dwordx4 v[82:85], v221, s[64:65]
	v_mfma_f32_32x32x16_bf16 v[18:33], v[102:105], v[98:101], v[18:33]
	global_load_dwordx4 v[78:81], v226, s[64:65]
	global_load_dwordx4 v[86:89], v222, s[64:65]
	v_mfma_f32_32x32x16_bf16 v[2:17], v[94:97], v[98:101], v[2:17]
	global_load_dwordx4 v[90:93], v227, s[64:65]
	global_load_dwordx4 v[110:113], v223, s[64:65]
	s_add_u32 s64, s64, 0x4000
	s_addc_u32 s65, s65, 0
	s_waitcnt lgkmcnt(0)
	s_barrier
	ds_read_b128 v[102:105], v168 offset:55296
	ds_read_b128 v[94:97], v168 offset:59904
	ds_read_b128 v[106:109], v169 offset:36864
	ds_read_b128 v[98:101], v169 offset:41472
	v_mfma_f32_32x32x16_bf16 v[50:65], v[172:175], v[180:183], v[50:65]
	v_mfma_f32_32x32x16_bf16 v[34:49], v[176:179], v[180:183], v[34:49]
	v_mfma_f32_32x32x16_bf16 v[18:33], v[172:175], v[184:187], v[18:33]
	v_mfma_f32_32x32x16_bf16 v[2:17], v[176:179], v[184:187], v[2:17]
	ds_read_b128 v[172:175], v168 offset:55328
	ds_read_b128 v[176:179], v168 offset:59936
	ds_read_b128 v[180:183], v169 offset:36896
	ds_read_b128 v[184:187], v169 offset:41504
	s_waitcnt lgkmcnt(4)
	v_mfma_f32_32x32x16_bf16 v[50:65], v[102:105], v[106:109], v[50:65]
	s_waitcnt vmcnt(7)
	ds_write_b128 v140, v[66:69]
	v_mfma_f32_32x32x16_bf16 v[34:49], v[94:97], v[106:109], v[34:49]
	s_waitcnt vmcnt(6)
	ds_write_b128 v140, v[74:77] offset:18432
	v_mfma_f32_32x32x16_bf16 v[18:33], v[102:105], v[98:101], v[18:33]
	s_waitcnt vmcnt(5)
	ds_write_b128 v142, v[70:73]
	v_mfma_f32_32x32x16_bf16 v[2:17], v[94:97], v[98:101], v[2:17]
	s_waitcnt vmcnt(4)
	ds_write_b128 v142, v[82:85] offset:18432
	ds_read_b128 v[102:105], v168 offset:55360
	ds_read_b128 v[94:97], v168 offset:59968
	ds_read_b128 v[106:109], v169 offset:36928
	ds_read_b128 v[98:101], v169 offset:41536
	s_waitcnt lgkmcnt(4)
	v_mfma_f32_32x32x16_bf16 v[50:65], v[172:175], v[180:183], v[50:65]
	s_waitcnt vmcnt(3)
	ds_write_b128 v144, v[78:81]
	v_mfma_f32_32x32x16_bf16 v[34:49], v[176:179], v[180:183], v[34:49]
	s_waitcnt vmcnt(2)
	ds_write_b128 v144, v[86:89] offset:18432
	v_mfma_f32_32x32x16_bf16 v[18:33], v[172:175], v[184:187], v[18:33]
	s_waitcnt vmcnt(1)
	ds_write_b128 v146, v[90:93]
	v_mfma_f32_32x32x16_bf16 v[2:17], v[176:179], v[184:187], v[2:17]
	s_waitcnt vmcnt(0)
	ds_write_b128 v146, v[110:113] offset:18432
	ds_read_b128 v[172:175], v168 offset:55392
	ds_read_b128 v[176:179], v168 offset:60000
	ds_read_b128 v[180:183], v169 offset:36960
	ds_read_b128 v[184:187], v169 offset:41568
	s_waitcnt lgkmcnt(8)
	v_mfma_f32_32x32x16_bf16 v[50:65], v[102:105], v[106:109], v[50:65]
	global_load_dwordx4 v[66:69], v224, s[64:65]
	global_load_dwordx4 v[74:77], v220, s[64:65]
	v_mfma_f32_32x32x16_bf16 v[34:49], v[94:97], v[106:109], v[34:49]
	global_load_dwordx4 v[70:73], v225, s[64:65]
	global_load_dwordx4 v[82:85], v221, s[64:65]
	v_mfma_f32_32x32x16_bf16 v[18:33], v[102:105], v[98:101], v[18:33]
	global_load_dwordx4 v[78:81], v226, s[64:65]
	global_load_dwordx4 v[86:89], v222, s[64:65]
	v_mfma_f32_32x32x16_bf16 v[2:17], v[94:97], v[98:101], v[2:17]
	global_load_dwordx4 v[90:93], v227, s[64:65]
	global_load_dwordx4 v[110:113], v223, s[64:65]
	s_add_u32 s64, s64, 0x4000
	s_addc_u32 s65, s65, 0
	s_waitcnt lgkmcnt(0)
	s_barrier
	ds_read_b128 v[102:105], v168 offset:18432
	ds_read_b128 v[94:97], v168 offset:23040
	ds_read_b128 v[106:109], v169
	ds_read_b128 v[98:101], v169 offset:4608
	v_mfma_f32_32x32x16_bf16 v[50:65], v[172:175], v[180:183], v[50:65]
	v_mfma_f32_32x32x16_bf16 v[34:49], v[176:179], v[180:183], v[34:49]
	v_mfma_f32_32x32x16_bf16 v[18:33], v[172:175], v[184:187], v[18:33]
	v_mfma_f32_32x32x16_bf16 v[2:17], v[176:179], v[184:187], v[2:17]
.Lk5f_loop:
	ds_read_b128 v[172:175], v168 offset:18464
	ds_read_b128 v[176:179], v168 offset:23072
	ds_read_b128 v[180:183], v169 offset:32
	ds_read_b128 v[184:187], v169 offset:4640
	s_waitcnt lgkmcnt(4)
	v_mfma_f32_32x32x16_bf16 v[50:65], v[102:105], v[106:109], v[50:65]
	s_waitcnt vmcnt(7)
	ds_write_b128 v140, v[66:69] offset:36864
	v_mfma_f32_32x32x16_bf16 v[34:49], v[94:97], v[106:109], v[34:49]
	s_waitcnt vmcnt(6)
	ds_write_b128 v140, v[74:77] offset:55296
	v_mfma_f32_32x32x16_bf16 v[18:33], v[102:105], v[98:101], v[18:33]
	s_waitcnt vmcnt(5)
	ds_write_b128 v142, v[70:73] offset:36864
	v_mfma_f32_32x32x16_bf16 v[2:17], v[94:97], v[98:101], v[2:17]
	s_waitcnt vmcnt(4)
	ds_write_b128 v142, v[82:85] offset:55296
	ds_read_b128 v[102:105], v168 offset:18496
	ds_read_b128 v[94:97], v168 offset:23104
	ds_read_b128 v[106:109], v169 offset:64
	ds_read_b128 v[98:101], v169 offset:4672
	s_waitcnt lgkmcnt(4)
	v_mfma_f32_32x32x16_bf16 v[50:65], v[172:175], v[180:183], v[50:65]
	s_waitcnt vmcnt(3)
	ds_write_b128 v144, v[78:81] offset:36864
	v_mfma_f32_32x32x16_bf16 v[34:49], v[176:179], v[180:183], v[34:49]
	s_waitcnt vmcnt(2)
	ds_write_b128 v144, v[86:89] offset:55296
	v_mfma_f32_32x32x16_bf16 v[18:33], v[172:175], v[184:187], v[18:33]
	s_waitcnt vmcnt(1)
	ds_write_b128 v146, v[90:93] offset:36864
	v_mfma_f32_32x32x16_bf16 v[2:17], v[176:179], v[184:187], v[2:17]
	s_waitcnt vmcnt(0)
	ds_write_b128 v146, v[110:113] offset:55296
	ds_read_b128 v[172:175], v168 offset:18528
	ds_read_b128 v[176:179], v168 offset:23136
	ds_read_b128 v[180:183], v169 offset:96
	ds_read_b128 v[184:187], v169 offset:4704
	s_waitcnt lgkmcnt(8)
	v_mfma_f32_32x32x16_bf16 v[50:65], v[102:105], v[106:109], v[50:65]
	global_load_dwordx4 v[66:69], v224, s[64:65]
	global_load_dwordx4 v[74:77], v220, s[64:65]
	v_mfma_f32_32x32x16_bf16 v[34:49], v[94:97], v[106:109], v[34:49]
	global_load_dwordx4 v[70:73], v225, s[64:65]
	global_load_dwordx4 v[82:85], v221, s[64:65]
	v_mfma_f32_32x32x16_bf16 v[18:33], v[102:105], v[98:101], v[18:33]
	global_load_dwordx4 v[78:81], v226, s[64:65]
	global_load_dwordx4 v[86:89], v222, s[64:65]
	v_mfma_f32_32x32x16_bf16 v[2:17], v[94:97], v[98:101], v[2:17]
	global_load_dwordx4 v[90:93], v227, s[64:65]
	global_load_dwordx4 v[110:113], v223, s[64:65]
	s_add_u32 s64, s64, 0x4000
	s_addc_u32 s65, s65, 0
	s_waitcnt lgkmcnt(0)
	s_barrier
	ds_read_b128 v[102:105], v168 offset:55296
	ds_read_b128 v[94:97], v168 offset:59904
	ds_read_b128 v[106:109], v169 offset:36864
	ds_read_b128 v[98:101], v169 offset:41472
	v_mfma_f32_32x32x16_bf16 v[50:65], v[172:175], v[180:183], v[50:65]
	v_mfma_f32_32x32x16_bf16 v[34:49], v[176:179], v[180:183], v[34:49]
	v_mfma_f32_32x32x16_bf16 v[18:33], v[172:175], v[184:187], v[18:33]
	v_mfma_f32_32x32x16_bf16 v[2:17], v[176:179], v[184:187], v[2:17]
	ds_read_b128 v[172:175], v168 offset:55328
	ds_read_b128 v[176:179], v168 offset:59936
	ds_read_b128 v[180:183], v169 offset:36896
	ds_read_b128 v[184:187], v169 offset:41504
	s_waitcnt lgkmcnt(4)
	v_mfma_f32_32x32x16_bf16 v[50:65], v[102:105], v[106:109], v[50:65]
	s_waitcnt vmcnt(7)
	ds_write_b128 v140, v[66:69]
	v_mfma_f32_32x32x16_bf16 v[34:49], v[94:97], v[106:109], v[34:49]
	s_waitcnt vmcnt(6)
	ds_write_b128 v140, v[74:77] offset:18432
	v_mfma_f32_32x32x16_bf16 v[18:33], v[102:105], v[98:101], v[18:33]
	s_waitcnt vmcnt(5)
	ds_write_b128 v142, v[70:73]
	v_mfma_f32_32x32x16_bf16 v[2:17], v[94:97], v[98:101], v[2:17]
	s_waitcnt vmcnt(4)
	ds_write_b128 v142, v[82:85] offset:18432
	ds_read_b128 v[102:105], v168 offset:55360
	ds_read_b128 v[94:97], v168 offset:59968
	ds_read_b128 v[106:109], v169 offset:36928
	ds_read_b128 v[98:101], v169 offset:41536
	s_waitcnt lgkmcnt(4)
	v_mfma_f32_32x32x16_bf16 v[50:65], v[172:175], v[180:183], v[50:65]
	s_waitcnt vmcnt(3)
	ds_write_b128 v144, v[78:81]
	v_mfma_f32_32x32x16_bf16 v[34:49], v[176:179], v[180:183], v[34:49]
	s_waitcnt vmcnt(2)
	ds_write_b128 v144, v[86:89] offset:18432
	v_mfma_f32_32x32x16_bf16 v[18:33], v[172:175], v[184:187], v[18:33]
	s_waitcnt vmcnt(1)
	ds_write_b128 v146, v[90:93]
	v_mfma_f32_32x32x16_bf16 v[2:17], v[176:179], v[184:187], v[2:17]
	s_waitcnt vmcnt(0)
	ds_write_b128 v146, v[110:113] offset:18432
	ds_read_b128 v[172:175], v168 offset:55392
	ds_read_b128 v[176:179], v168 offset:60000
	ds_read_b128 v[180:183], v169 offset:36960
	ds_read_b128 v[184:187], v169 offset:41568
	s_waitcnt lgkmcnt(8)
	v_mfma_f32_32x32x16_bf16 v[50:65], v[102:105], v[106:109], v[50:65]
	global_load_dwordx4 v[66:69], v224, s[64:65]
	global_load_dwordx4 v[74:77], v220, s[64:65]
	v_mfma_f32_32x32x16_bf16 v[34:49], v[94:97], v[106:109], v[34:49]
	global_load_dwordx4 v[70:73], v225, s[64:65]
	global_load_dwordx4 v[82:85], v221, s[64:65]
	v_mfma_f32_32x32x16_bf16 v[18:33], v[102:105], v[98:101], v[18:33]
	global_load_dwordx4 v[78:81], v226, s[64:65]
	global_load_dwordx4 v[86:89], v222, s[64:65]
	v_mfma_f32_32x32x16_bf16 v[2:17], v[94:97], v[98:101], v[2:17]
	global_load_dwordx4 v[90:93], v227, s[64:65]
	global_load_dwordx4 v[110:113], v223, s[64:65]
	s_add_u32 s64, s64, 0x4000
	s_addc_u32 s65, s65, 0
	s_waitcnt lgkmcnt(0)
	s_barrier
	ds_read_b128 v[102:105], v168 offset:18432
	ds_read_b128 v[94:97], v168 offset:23040
	ds_read_b128 v[106:109], v169
	ds_read_b128 v[98:101], v169 offset:4608
	v_mfma_f32_32x32x16_bf16 v[50:65], v[172:175], v[180:183], v[50:65]
	v_mfma_f32_32x32x16_bf16 v[34:49], v[176:179], v[180:183], v[34:49]
	v_mfma_f32_32x32x16_bf16 v[18:33], v[172:175], v[184:187], v[18:33]
	v_mfma_f32_32x32x16_bf16 v[2:17], v[176:179], v[184:187], v[2:17]
	s_sub_u32 s66, s66, 1
	s_cmp_lg_u32 s66, 0
	s_cbranch_scc1 .Lk5f_loop
	s_branch .LBB0_679
.Lk5_masked:
	ds_read_b128 v[172:175], v168 offset:18464
	ds_read_b128 v[176:179], v168 offset:23072
	ds_read_b128 v[180:183], v169 offset:32
	ds_read_b128 v[184:187], v169 offset:4640
	s_waitcnt lgkmcnt(4)
	v_mfma_f32_32x32x16_bf16 v[50:65], v[102:105], v[106:109], 0
	s_waitcnt vmcnt(7)
	ds_write_b128 v140, v[66:69] offset:36864
	v_mfma_f32_32x32x16_bf16 v[34:49], v[94:97], v[106:109], 0
	s_waitcnt vmcnt(6)
	ds_write_b128 v140, v[74:77] offset:55296
	v_mfma_f32_32x32x16_bf16 v[18:33], v[102:105], v[98:101], 0
	s_waitcnt vmcnt(5)
	ds_write_b128 v142, v[70:73] offset:36864
	v_mfma_f32_32x32x16_bf16 v[2:17], v[94:97], v[98:101], 0
	s_waitcnt vmcnt(4)
	ds_write_b128 v142, v[82:85] offset:55296
	ds_read_b128 v[102:105], v168 offset:18496
	ds_read_b128 v[94:97], v168 offset:23104
	ds_read_b128 v[106:109], v169 offset:64
	ds_read_b128 v[98:101], v169 offset:4672
	s_waitcnt lgkmcnt(4)
	v_mfma_f32_32x32x16_bf16 v[50:65], v[172:175], v[180:183], v[50:65]
	s_waitcnt vmcnt(3)
	ds_write_b128 v144, v[78:81] offset:36864
	v_mfma_f32_32x32x16_bf16 v[34:49], v[176:179], v[180:183], v[34:49]
	s_waitcnt vmcnt(2)
	ds_write_b128 v144, v[86:89] offset:55296
	v_mfma_f32_32x32x16_bf16 v[18:33], v[172:175], v[184:187], v[18:33]
	s_waitcnt vmcnt(1)
	ds_write_b128 v146, v[90:93] offset:36864
	v_mfma_f32_32x32x16_bf16 v[2:17], v[176:179], v[184:187], v[2:17]
	s_waitcnt vmcnt(0)
	ds_write_b128 v146, v[110:113] offset:55296
	ds_read_b128 v[172:175], v168 offset:18528
	ds_read_b128 v[176:179], v168 offset:23136
	ds_read_b128 v[180:183], v169 offset:96
	ds_read_b128 v[184:187], v169 offset:4704
	s_waitcnt lgkmcnt(8)
	v_mfma_f32_32x32x16_bf16 v[50:65], v[102:105], v[106:109], v[50:65]
	s_mov_b64 exec, s[4:5]
	global_load_dwordx4 v[66:69], v224, s[64:65]
	s_mov_b64 exec, -1
	global_load_dwordx4 v[74:77], v220, s[64:65]
	v_mfma_f32_32x32x16_bf16 v[34:49], v[94:97], v[106:109], v[34:49]
	s_mov_b64 exec, s[6:7]
	global_load_dwordx4 v[70:73], v225, s[64:65]
	s_mov_b64 exec, -1
	global_load_dwordx4 v[82:85], v221, s[64:65]
	v_mfma_f32_32x32x16_bf16 v[18:33], v[102:105], v[98:101], v[18:33]
	s_mov_b64 exec, s[8:9]
	global_load_dwordx4 v[78:81], v226, s[64:65]
	s_mov_b64 exec, -1
	global_load_dwordx4 v[86:89], v222, s[64:65]
	v_mfma_f32_32x32x16_bf16 v[2:17], v[94:97], v[98:101], v[2:17]
	s_mov_b64 exec, s[10:11]
	global_load_dwordx4 v[90:93], v227, s[64:65]
	s_mov_b64 exec, -1
	global_load_dwordx4 v[110:113], v223, s[64:65]
	s_add_u32 s64, s64, 0x4000
	s_addc_u32 s65, s65, 0
	s_waitcnt lgkmcnt(0)
	s_barrier
	ds_read_b128 v[102:105], v168 offset:55296
	ds_read_b128 v[94:97], v168 offset:59904
	ds_read_b128 v[106:109], v169 offset:36864
	ds_read_b128 v[98:101], v169 offset:41472
	v_mfma_f32_32x32x16_bf16 v[50:65], v[172:175], v[180:183], v[50:65]
	v_mfma_f32_32x32x16_bf16 v[34:49], v[176:179], v[180:183], v[34:49]
	v_mfma_f32_32x32x16_bf16 v[18:33], v[172:175], v[184:187], v[18:33]
	v_mfma_f32_32x32x16_bf16 v[2:17], v[176:179], v[184:187], v[2:17]
	ds_read_b128 v[172:175], v168 offset:55328
	ds_read_b128 v[176:179], v168 offset:59936
	ds_read_b128 v[180:183], v169 offset:36896
	ds_read_b128 v[184:187], v169 offset:41504
	s_waitcnt lgkmcnt(4)
	v_mfma_f32_32x32x16_bf16 v[50:65], v[102:105], v[106:109], v[50:65]
	s_waitcnt vmcnt(7)
	ds_write_b128 v140, v[66:69]
	v_mfma_f32_32x32x16_bf16 v[34:49], v[94:97], v[106:109], v[34:49]
	s_waitcnt vmcnt(6)
	ds_write_b128 v140, v[74:77] offset:18432
	v_mfma_f32_32x32x16_bf16 v[18:33], v[102:105], v[98:101], v[18:33]
	s_waitcnt vmcnt(5)
	ds_write_b128 v142, v[70:73]
	v_mfma_f32_32x32x16_bf16 v[2:17], v[94:97], v[98:101], v[2:17]
	s_waitcnt vmcnt(4)
	ds_write_b128 v142, v[82:85] offset:18432
	ds_read_b128 v[102:105], v168 offset:55360
	ds_read_b128 v[94:97], v168 offset:59968
	ds_read_b128 v[106:109], v169 offset:36928
	ds_read_b128 v[98:101], v169 offset:41536
	s_waitcnt lgkmcnt(4)
	v_mfma_f32_32x32x16_bf16 v[50:65], v[172:175], v[180:183], v[50:65]
	s_waitcnt vmcnt(3)
	ds_write_b128 v144, v[78:81]
	v_mfma_f32_32x32x16_bf16 v[34:49], v[176:179], v[180:183], v[34:49]
	s_waitcnt vmcnt(2)
	ds_write_b128 v144, v[86:89] offset:18432
	v_mfma_f32_32x32x16_bf16 v[18:33], v[172:175], v[184:187], v[18:33]
	s_waitcnt vmcnt(1)
	ds_write_b128 v146, v[90:93]
	v_mfma_f32_32x32x16_bf16 v[2:17], v[176:179], v[184:187], v[2:17]
	s_waitcnt vmcnt(0)
	ds_write_b128 v146, v[110:113] offset:18432
	ds_read_b128 v[172:175], v168 offset:55392
	ds_read_b128 v[176:179], v168 offset:60000
	ds_read_b128 v[180:183], v169 offset:36960
	ds_read_b128 v[184:187], v169 offset:41568
	s_waitcnt lgkmcnt(8)
	v_mfma_f32_32x32x16_bf16 v[50:65], v[102:105], v[106:109], v[50:65]
	s_mov_b64 exec, s[4:5]
	global_load_dwordx4 v[66:69], v224, s[64:65]
	s_mov_b64 exec, -1
	global_load_dwordx4 v[74:77], v220, s[64:65]
	v_mfma_f32_32x32x16_bf16 v[34:49], v[94:97], v[106:109], v[34:49]
	s_mov_b64 exec, s[6:7]
	global_load_dwordx4 v[70:73], v225, s[64:65]
	s_mov_b64 exec, -1
	global_load_dwordx4 v[82:85], v221, s[64:65]
	v_mfma_f32_32x32x16_bf16 v[18:33], v[102:105], v[98:101], v[18:33]
	s_mov_b64 exec, s[8:9]
	global_load_dwordx4 v[78:81], v226, s[64:65]
	s_mov_b64 exec, -1
	global_load_dwordx4 v[86:89], v222, s[64:65]
	v_mfma_f32_32x32x16_bf16 v[2:17], v[94:97], v[98:101], v[2:17]
	s_mov_b64 exec, s[10:11]
	global_load_dwordx4 v[90:93], v227, s[64:65]
	s_mov_b64 exec, -1
	global_load_dwordx4 v[110:113], v223, s[64:65]
	s_add_u32 s64, s64, 0x4000
	s_addc_u32 s65, s65, 0
	s_waitcnt lgkmcnt(0)
	s_barrier
	ds_read_b128 v[102:105], v168 offset:18432
	ds_read_b128 v[94:97], v168 offset:23040
	ds_read_b128 v[106:109], v169
	ds_read_b128 v[98:101], v169 offset:4608
	v_mfma_f32_32x32x16_bf16 v[50:65], v[172:175], v[180:183], v[50:65]
	v_mfma_f32_32x32x16_bf16 v[34:49], v[176:179], v[180:183], v[34:49]
	v_mfma_f32_32x32x16_bf16 v[18:33], v[172:175], v[184:187], v[18:33]
	v_mfma_f32_32x32x16_bf16 v[2:17], v[176:179], v[184:187], v[2:17]

.LBB0_2386:
	s_or_b64 exec, exec, s[22:23]
	v_add_co_u32_e32 v4, vcc, 0x7000, v30
	s_mul_i32 s22, s38, 62
	s_nop 0
	v_addc_co_u32_e32 v5, vcc, 0, v31, vcc
	global_load_dwordx4 v[110:113], v[4:5], off
	v_ashrrev_i32_e32 v4, 3, v41
	s_add_i32 s22, s24, s22
	v_lshrrev_b32_e32 v116, 4, v4
	s_add_i32 s22, s22, s37
	v_ashrrev_i32_e32 v8, 3, v40
	v_lshlrev_b64 v[4:5], 18, v[116:117]
	s_lshl_b32 s22, s22, 1
	v_lshl_add_u64 v[2:3], v[2:3], 1, v[4:5]
	v_lshrrev_b32_e32 v116, 4, v8
	v_subrev_u16_e32 v4, s22, v163
	v_ashrrev_i32_e32 v7, 3, v39
	v_lshl_add_u64 v[128:129], v[122:123], 0, v[2:3]
	v_lshlrev_b64 v[2:3], 18, v[116:117]
	v_and_b32_e32 v4, 0x7f, v4
	s_waitcnt lgkmcnt(0)
	s_barrier
	ds_read_b128 v[102:105], v168 offset:18432
	ds_read_b128 v[94:97], v168 offset:23040
	ds_read_b128 v[106:109], v169
	ds_read_b128 v[98:101], v169 offset:4608
	v_lshl_or_b32 v2, v4, 7, v2
	v_lshrrev_b32_e32 v116, 4, v7
	v_subrev_u16_e32 v4, s22, v164
	v_ashrrev_i32_e32 v6, 3, v38
	v_lshl_add_u64 v[130:131], v[122:123], 0, v[2:3]
	v_lshlrev_b64 v[2:3], 18, v[116:117]
	v_and_b32_e32 v4, 0x7f, v4
	v_lshl_or_b32 v2, v4, 7, v2
	v_lshrrev_b32_e32 v116, 4, v6
	v_subrev_u16_e32 v4, s22, v165
	v_lshl_add_u64 v[132:133], v[122:123], 0, v[2:3]
	v_lshlrev_b64 v[2:3], 18, v[116:117]
	v_and_b32_e32 v4, 0x7f, v4
	v_lshl_or_b32 v2, v4, 7, v2
	v_lshl_add_u64 v[134:135], v[122:123], 0, v[2:3]
	s_mov_b32 s19, 0
	v_lshl_add_u64 v[136:137], v[124:125], 0, s[20:21]
	s_mov_b64 s[20:21], 0
	s_sub_u32 s62, 0x1b2c000, s34
	v_add_u32_e32 v220, s62, v136
	s_sub_u32 s62, 0x1b2d000, s34
	v_add_u32_e32 v221, s62, v136
	s_sub_u32 s62, 0x1b2e000, s34
	v_add_u32_e32 v222, s62, v136
	s_sub_u32 s62, 0x1b2f000, s34
	v_add_u32_e32 v223, s62, v136
	v_subrev_u32_e32 v224, s34, v134
	v_subrev_u32_e32 v225, s34, v132
	v_subrev_u32_e32 v226, s34, v130
	v_subrev_u32_e32 v227, s34, v128
	s_mov_b32 s64, s34
	s_mov_b32 s65, s35
	s_mov_b32 s66, 6
	s_and_b64 s[62:63], s[4:5], s[6:7]
	s_and_b64 s[62:63], s[62:63], s[8:9]
	s_and_b64 s[62:63], s[62:63], s[10:11]
	s_cmp_eq_u64 s[62:63], -1
	s_cbranch_scc0 .Lk12_masked
	ds_read_b128 v[172:175], v168 offset:18464
	ds_read_b128 v[176:179], v168 offset:23072
	ds_read_b128 v[180:183], v169 offset:32
	ds_read_b128 v[184:187], v169 offset:4640
	s_waitcnt lgkmcnt(4)
	v_mfma_f32_32x32x16_bf16 v[50:65], v[102:105], v[106:109], 0
	s_waitcnt vmcnt(7)
	ds_write_b128 v140, v[66:69] offset:36864
	v_mfma_f32_32x32x16_bf16 v[34:49], v[94:97], v[106:109], 0
	s_waitcnt vmcnt(6)
	ds_write_b128 v140, v[74:77] offset:55296
	v_mfma_f32_32x32x16_bf16 v[18:33], v[102:105], v[98:101], 0
	s_waitcnt vmcnt(5)
	ds_write_b128 v142, v[70:73] offset:36864
	v_mfma_f32_32x32x16_bf16 v[2:17], v[94:97], v[98:101], 0
	s_waitcnt vmcnt(4)
	ds_write_b128 v142, v[82:85] offset:55296
	ds_read_b128 v[102:105], v168 offset:18496
	ds_read_b128 v[94:97], v168 offset:23104
	ds_read_b128 v[106:109], v169 offset:64
	ds_read_b128 v[98:101], v169 offset:4672
	s_waitcnt lgkmcnt(4)
	v_mfma_f32_32x32x16_bf16 v[50:65], v[172:175], v[180:183], v[50:65]
	s_waitcnt vmcnt(3)
	ds_write_b128 v144, v[78:81] offset:36864
	v_mfma_f32_32x32x16_bf16 v[34:49], v[176:179], v[180:183], v[34:49]
	s_waitcnt vmcnt(2)
	ds_write_b128 v144, v[86:89] offset:55296
	v_mfma_f32_32x32x16_bf16 v[18:33], v[172:175], v[184:187], v[18:33]
	s_waitcnt vmcnt(1)
	ds_write_b128 v146, v[90:93] offset:36864
	v_mfma_f32_32x32x16_bf16 v[2:17], v[176:179], v[184:187], v[2:17]
	s_waitcnt vmcnt(0)
	ds_write_b128 v146, v[110:113] offset:55296
	ds_read_b128 v[172:175], v168 offset:18528
	ds_read_b128 v[176:179], v168 offset:23136
	ds_read_b128 v[180:183], v169 offset:96
	ds_read_b128 v[184:187], v169 offset:4704
	s_waitcnt lgkmcnt(8)
	v_mfma_f32_32x32x16_bf16 v[50:65], v[102:105], v[106:109], v[50:65]
	global_load_dwordx4 v[66:69], v224, s[64:65]
	global_load_dwordx4 v[74:77], v220, s[64:65]
	v_mfma_f32_32x32x16_bf16 v[34:49], v[94:97], v[106:109], v[34:49]
	global_load_dwordx4 v[70:73], v225, s[64:65]
	global_load_dwordx4 v[82:85], v221, s[64:65]
	v_mfma_f32_32x32x16_bf16 v[18:33], v[102:105], v[98:101], v[18:33]
	global_load_dwordx4 v[78:81], v226, s[64:65]
	global_load_dwordx4 v[86:89], v222, s[64:65]
	v_mfma_f32_32x32x16_bf16 v[2:17], v[94:97], v[98:101], v[2:17]
	global_load_dwordx4 v[90:93], v227, s[64:65]
	global_load_dwordx4 v[110:113], v223, s[64:65]
	s_add_u32 s64, s64, 0x4000
	s_addc_u32 s65, s65, 0
	s_waitcnt lgkmcnt(0)
	s_barrier
	ds_read_b128 v[102:105], v168 offset:55296
	ds_read_b128 v[94:97], v168 offset:59904
	ds_read_b128 v[106:109], v169 offset:36864
	ds_read_b128 v[98:101], v169 offset:41472
	v_mfma_f32_32x32x16_bf16 v[50:65], v[172:175], v[180:183], v[50:65]
	v_mfma_f32_32x32x16_bf16 v[34:49], v[176:179], v[180:183], v[34:49]
	v_mfma_f32_32x32x16_bf16 v[18:33], v[172:175], v[184:187], v[18:33]
	v_mfma_f32_32x32x16_bf16 v[2:17], v[176:179], v[184:187], v[2:17]
	ds_read_b128 v[172:175], v168 offset:55328
	ds_read_b128 v[176:179], v168 offset:59936
	ds_read_b128 v[180:183], v169 offset:36896
	ds_read_b128 v[184:187], v169 offset:41504
	s_waitcnt lgkmcnt(4)
	v_mfma_f32_32x32x16_bf16 v[50:65], v[102:105], v[106:109], v[50:65]
	s_waitcnt vmcnt(7)
	ds_write_b128 v140, v[66:69]
	v_mfma_f32_32x32x16_bf16 v[34:49], v[94:97], v[106:109], v[34:49]
	s_waitcnt vmcnt(6)
	ds_write_b128 v140, v[74:77] offset:18432
	v_mfma_f32_32x32x16_bf16 v[18:33], v[102:105], v[98:101], v[18:33]
	s_waitcnt vmcnt(5)
	ds_write_b128 v142, v[70:73]
	v_mfma_f32_32x32x16_bf16 v[2:17], v[94:97], v[98:101], v[2:17]
	s_waitcnt vmcnt(4)
	ds_write_b128 v142, v[82:85] offset:18432
	ds_read_b128 v[102:105], v168 offset:55360
	ds_read_b128 v[94:97], v168 offset:59968
	ds_read_b128 v[106:109], v169 offset:36928
	ds_read_b128 v[98:101], v169 offset:41536
	s_waitcnt lgkmcnt(4)
	v_mfma_f32_32x32x16_bf16 v[50:65], v[172:175], v[180:183], v[50:65]
	s_waitcnt vmcnt(3)
	ds_write_b128 v144, v[78:81]
	v_mfma_f32_32x32x16_bf16 v[34:49], v[176:179], v[180:183], v[34:49]
	s_waitcnt vmcnt(2)
	ds_write_b128 v144, v[86:89] offset:18432
	v_mfma_f32_32x32x16_bf16 v[18:33], v[172:175], v[184:187], v[18:33]
	s_waitcnt vmcnt(1)
	ds_write_b128 v146, v[90:93]
	v_mfma_f32_32x32x16_bf16 v[2:17], v[176:179], v[184:187], v[2:17]
	s_waitcnt vmcnt(0)
	ds_write_b128 v146, v[110:113] offset:18432
	ds_read_b128 v[172:175], v168 offset:55392
	ds_read_b128 v[176:179], v168 offset:60000
	ds_read_b128 v[180:183], v169 offset:36960
	ds_read_b128 v[184:187], v169 offset:41568
	s_waitcnt lgkmcnt(8)
	v_mfma_f32_32x32x16_bf16 v[50:65], v[102:105], v[106:109], v[50:65]
	global_load_dwordx4 v[66:69], v224, s[64:65]
	global_load_dwordx4 v[74:77], v220, s[64:65]
	v_mfma_f32_32x32x16_bf16 v[34:49], v[94:97], v[106:109], v[34:49]
	global_load_dwordx4 v[70:73], v225, s[64:65]
	global_load_dwordx4 v[82:85], v221, s[64:65]
	v_mfma_f32_32x32x16_bf16 v[18:33], v[102:105], v[98:101], v[18:33]
	global_load_dwordx4 v[78:81], v226, s[64:65]
	global_load_dwordx4 v[86:89], v222, s[64:65]
	v_mfma_f32_32x32x16_bf16 v[2:17], v[94:97], v[98:101], v[2:17]
	global_load_dwordx4 v[90:93], v227, s[64:65]
	global_load_dwordx4 v[110:113], v223, s[64:65]
	s_add_u32 s64, s64, 0x4000
	s_addc_u32 s65, s65, 0
	s_waitcnt lgkmcnt(0)
	s_barrier
	ds_read_b128 v[102:105], v168 offset:18432
	ds_read_b128 v[94:97], v168 offset:23040
	ds_read_b128 v[106:109], v169
	ds_read_b128 v[98:101], v169 offset:4608
	v_mfma_f32_32x32x16_bf16 v[50:65], v[172:175], v[180:183], v[50:65]
	v_mfma_f32_32x32x16_bf16 v[34:49], v[176:179], v[180:183], v[34:49]
	v_mfma_f32_32x32x16_bf16 v[18:33], v[172:175], v[184:187], v[18:33]
	v_mfma_f32_32x32x16_bf16 v[2:17], v[176:179], v[184:187], v[2:17]
